# v80 + MLA progress flags written with the full wave (same address, same value) instead of a single-lane exec round trip: 9 fewer SALU per key tile
# baseline (speedup 1.0000x reference)
; DI void kv96x8_store(const KVR8& R, bf16_t* sK, bf16_t* sVt, int tid) {
;   const int row = tid >> 3, kc = tid & 7, rr = (tid & 255) >> 2, rc = tid & 3;
;   *(u32x4*)(sK + row * 104 + kc * 8) = R.k0;
;   if (tid < 256) *(u32x4*)(sK + rr * 104 + 64 + rc * 8) = R.k2;
;   *(u32x4*)(sVt + row * 72 + kc * 8) = R.v0;
; }
; DI void phase_attn_mla(const Params& P, bf16_t* og, unsigned char* smem, int L, int G) {
;     ...
;       if (j < jhi) kv96x8_store(R, sK + (cb ^ 1) * KVB96, sVt + (cb ^ 1) * KVB96, tid);
.Lmy_mla_go:
	s_cmp_ge_u32 s26, s19
	s_cbranch_scc1 .LBB0_783
	s_xor_b32 s24, s40, 1
	s_mulk_i32 s24, 0x2c00
	s_lshl_b32 s25, s24, 1
	v_add3_u32 v0, s25, v180, v158
	s_waitcnt vmcnt(1)
	ds_write_b128 v0, v[108:111]
	s_and_saveexec_b64 s[22:23], s[12:13]
	v_add3_u32 v0, s25, v151, v160
	ds_write_b128 v0, v[104:107] offset:128
	s_or_b64 exec, exec, s[22:23]
	v_lshl_add_u32 v0, s24, 1, v142
	s_waitcnt vmcnt(0)
	ds_write_b128 v0, v[112:115] offset:13312
	ds_write_b32 v252, v254 offset:32

; template <int DQK, bool MASKED, int MODE, class MF>
; DI void attn_step(const bf16_t* sK, const bf16_t* sVt, const bf16x8 (&qf)[DQK / 16], f32x16& o0, f32x16& o1, float& m, float& l,
;                   float sc, const MF& mf, int lane, f32x16 (&s)[2], float invl, bool lanevalid = true) {
;     ...
;   bf16x8 kf[2][DQK / 16];
; #pragma unroll
;   for (int sub = 0; sub < 2; ++sub)
; #pragma unroll
;     for (int ks = 0; ks < DQK / 16; ++ks) kf[sub][ks] = *(const bf16x8*)(sK + (sub * 32 + pr) * KST + ks * 16 + 8 * h);
;   __builtin_amdgcn_sched_barrier(0);
; #pragma unroll
;   for (int q = 0; q < 16; ++q) { s[0][q] = 0.f; s[1][q] = 0.f; }
; #pragma unroll
;   for (int ks = 0; ks < DQK / 16; ++ks) {
;     s[0] = MFMA(kf[0][ks], qf[ks], s[0]);
;     s[1] = MFMA(kf[1][ks], qf[ks], s[1]);
;   }
;   bf16x8 vf[2][2][2];
;   if (MODE != 1) {
; #pragma unroll
;     for (int sub = 0; sub < 2; ++sub)
; #pragma unroll
;       for (int s2 = 0; s2 < 2; ++s2) {
;         vf[sub][s2][0] = *(const bf16x8*)(sVt + r * 72 + sub * 32 + s2 * 16 + 8 * h);
;         vf[sub][s2][1] = *(const bf16x8*)(sVt + (32 + r) * 72 + sub * 32 + s2 * 16 + 8 * h);
;       }
;     __builtin_amdgcn_sched_barrier(0);
;   }
;   float mxr = -3.0e38f;
; #pragma unroll
;   for (int sub = 0; sub < 2; ++sub)
; #pragma unroll
;     for (int q = 0; q < 16; ++q) {
;       if (MASKED) { const int kk = sub * 32 + 16 * (q >> 3) + 8 * h + (q & 7); s[sub][q] = mf(kk) ? s[sub][q] : -3.0e38f; }
;       if (MODE != 2) mxr = fmaxf(mxr, s[sub][q]);
;     }
;   float alpha = 1.f;
;   if (MODE != 2) {
;     float mx = fmaxf(m, mxr * sc);
;     mx = fmaxf(mx, shx(mx, 32));
;     if (!MASKED) mx = lanevalid ? mx : m;
;     alpha = fexp2(m - mx);
;     m = mx;
;   }
;   const float moff = (!MASKED && !lanevalid) ? 1.0e30f : m;
;   float ps = 0.f;
; #pragma unroll
;   for (int sub = 0; sub < 2; ++sub)
; #pragma unroll
;     for (int q = 0; q < 16; ++q) {
;       float pv = fexp2(__builtin_fmaf(s[sub][q], sc, -moff));
;       if (MASKED && MODE != 0) pv = (s[sub][q] > -1.0e38f) ? pv : 0.f;
;       if (MODE == 2) pv *= invl;
;       s[sub][q] = pv;
;       ps += pv;
;     }
;   if (MODE != 2) {
;     ps += shx(ps, 32);
;     l = l * alpha + ps;
;   }
;   if (MODE == 1) return;
;   if (MODE == 0) {
; #pragma unroll
;     for (int q = 0; q < 16; ++q) { o0[q] *= alpha; o1[q] *= alpha; }
.LBB0_785:
	v_cmp_le_i32_e32 vcc, s14, v163
	s_and_saveexec_b64 s[22:23], vcc
	s_cbranch_execz .Lmy_mla_skip
	s_add_i32 s24, s14, 63
	s_mulk_i32 s40, 0x2c00
	v_cmp_le_i32_e32 vcc, s24, v162
	s_lshl_b32 s39, s40, 1
	v_max_f32_e32 v0, v186, v186
	s_and_saveexec_b64 s[24:25], vcc
	s_xor_b64 s[24:25], exec, s[24:25]
	s_cbranch_execz .LBB0_788
	v_lshl_add_u32 v14, s40, 1, v143
	ds_read_b128 v[2:5], v14
	ds_read_b128 v[6:9], v14 offset:32
	ds_read_b128 v[10:13], v14 offset:64
	ds_read_b128 v[116:119], v14 offset:96
	ds_read_b128 v[120:123], v14 offset:128
	ds_read_b128 v[124:127], v14 offset:160
	ds_read_b128 v[48:51], v14 offset:6656
	ds_read_b128 v[128:131], v14 offset:6688
	ds_read_b128 v[132:135], v14 offset:6720
	ds_read_b128 v[188:191], v14 offset:6752
	ds_read_b128 v[194:197], v14 offset:6784
	ds_read_b128 v[198:201], v14 offset:6816
	s_waitcnt lgkmcnt(11)
	v_mfma_f32_32x32x16_bf16 v[64:79], v[2:5], v[100:103], 0
	v_add3_u32 v2, s39, v172, v156
	v_add3_u32 v3, s39, v173, v156
	s_waitcnt lgkmcnt(10)
	v_mfma_f32_32x32x16_bf16 v[64:79], v[6:9], v[80:83], v[64:79]
	s_waitcnt lgkmcnt(5)
	v_mfma_f32_32x32x16_bf16 v[48:63], v[48:51], v[100:103], 0
	v_mfma_f32_32x32x16_bf16 v[64:79], v[10:13], v[84:87], v[64:79]
	s_waitcnt lgkmcnt(4)
	v_mfma_f32_32x32x16_bf16 v[48:63], v[128:131], v[80:83], v[48:63]
	v_mfma_f32_32x32x16_bf16 v[64:79], v[116:119], v[88:91], v[64:79]
	s_waitcnt lgkmcnt(3)
	v_mfma_f32_32x32x16_bf16 v[48:63], v[132:135], v[84:87], v[48:63]
	v_mfma_f32_32x32x16_bf16 v[64:79], v[120:123], v[92:95], v[64:79]
	s_waitcnt lgkmcnt(2)
	v_mfma_f32_32x32x16_bf16 v[48:63], v[188:191], v[88:91], v[48:63]
	v_mfma_f32_32x32x16_bf16 v[64:79], v[124:127], v[96:99], v[64:79]
	ds_read_b128 v[132:135], v2 offset:13312
	ds_read_b128 v[124:127], v2 offset:13344
	ds_read_b128 v[128:131], v3 offset:13312
	ds_read_b128 v[120:123], v3 offset:13344
	ds_read_b128 v[116:119], v2 offset:13376
	ds_read_b128 v[6:9], v2 offset:13408
	ds_read_b128 v[10:13], v3 offset:13376
	ds_read_b128 v[2:5], v3 offset:13408
	s_waitcnt lgkmcnt(9)
	v_mfma_f32_32x32x16_bf16 v[48:63], v[194:197], v[92:95], v[48:63]
	s_waitcnt lgkmcnt(8)
	v_mfma_f32_32x32x16_bf16 v[48:63], v[198:201], v[96:99], v[48:63]
	v_max3_f32 v14, v64, s36, v65
	v_max3_f32 v14, v14, v66, v67
	v_max3_f32 v14, v14, v68, v69
	v_max3_f32 v14, v14, v70, v71
	v_max3_f32 v14, v14, v72, v73
	v_max3_f32 v14, v14, v74, v75
	v_max3_f32 v14, v14, v76, v77
	v_max3_f32 v14, v14, v78, v79
	s_nop 3
	v_max3_f32 v14, v14, v48, v49
	v_max3_f32 v14, v14, v50, v51
	v_max3_f32 v14, v14, v52, v53
	v_max3_f32 v14, v14, v54, v55
	v_max3_f32 v14, v14, v56, v57
	v_max3_f32 v14, v14, v58, v59
	v_max3_f32 v14, v14, v60, v61
	v_max3_f32 v14, v14, v62, v63
	v_mul_f32_e32 v14, 0x3e16c740, v14
	v_cmp_lt_i32_e32 vcc, v183, v184
	v_max_f32_e32 v0, v0, v14
	s_nop 0
	v_cndmask_b32_e32 v14, v182, v183, vcc
	v_lshlrev_b32_e32 v14, 2, v14
	ds_bpermute_b32 v15, v14, v0
	s_waitcnt lgkmcnt(0)
	ds_write_b32 v252, v254
	v_max_f32_e32 v15, v15, v15
	v_max_f32_e32 v15, v0, v15
	v_fma_f32 v0, v64, s37, -v15
	v_fma_f32 v64, v65, s37, -v15
	v_exp_f32_e32 v65, v0
	v_exp_f32_e32 v64, v64
	v_fma_f32 v0, v66, s37, -v15
	v_exp_f32_e32 v66, v0
	v_fma_f32 v67, v67, s37, -v15
	v_exp_f32_e32 v67, v67
	v_fma_f32 v68, v68, s37, -v15
	v_sub_f32_e32 v0, v186, v15
	v_add_f32_e32 v186, 0, v65
	v_exp_f32_e32 v68, v68
	v_fma_f32 v69, v69, s37, -v15
	v_add_f32_e32 v186, v64, v186
	v_exp_f32_e32 v69, v69
	v_fma_f32 v70, v70, s37, -v15
	v_add_f32_e32 v186, v66, v186
	v_exp_f32_e32 v70, v70
	v_fma_f32 v71, v71, s37, -v15
	v_add_f32_e32 v186, v67, v186
	v_exp_f32_e32 v71, v71
	v_fma_f32 v72, v72, s37, -v15
	v_add_f32_e32 v186, v68, v186
	v_exp_f32_e32 v72, v72
	v_fma_f32 v73, v73, s37, -v15
	v_add_f32_e32 v186, v69, v186
	v_exp_f32_e32 v73, v73
	v_fma_f32 v74, v74, s37, -v15
	v_add_f32_e32 v186, v70, v186
	v_exp_f32_e32 v74, v74
	v_fma_f32 v75, v75, s37, -v15
	v_add_f32_e32 v186, v71, v186
	v_exp_f32_e32 v75, v75
	v_fma_f32 v76, v76, s37, -v15
	v_add_f32_e32 v186, v72, v186
	v_exp_f32_e32 v76, v76
	v_fma_f32 v77, v77, s37, -v15
	v_add_f32_e32 v186, v73, v186
	v_exp_f32_e32 v77, v77
	v_fma_f32 v78, v78, s37, -v15
	v_add_f32_e32 v186, v74, v186
	v_exp_f32_e32 v78, v78
	v_fma_f32 v79, v79, s37, -v15
	v_add_f32_e32 v186, v75, v186
	v_exp_f32_e32 v79, v79
	v_fma_f32 v48, v48, s37, -v15
	v_add_f32_e32 v186, v76, v186
	v_exp_f32_e32 v187, v48
	v_fma_f32 v48, v49, s37, -v15
	v_add_f32_e32 v186, v77, v186
	v_exp_f32_e32 v188, v48
	v_fma_f32 v48, v50, s37, -v15
	v_add_f32_e32 v186, v78, v186
	v_exp_f32_e32 v189, v48
	v_fma_f32 v49, v51, s37, -v15
	v_add_f32_e32 v48, v79, v186
	v_exp_f32_e32 v186, v49
	v_fma_f32 v49, v52, s37, -v15
	v_add_f32_e32 v48, v187, v48
	v_exp_f32_e32 v52, v49
	v_fma_f32 v49, v53, s37, -v15
	v_add_f32_e32 v48, v188, v48
	v_exp_f32_e32 v53, v49
	v_fma_f32 v49, v54, s37, -v15
	v_add_f32_e32 v48, v189, v48
	v_exp_f32_e32 v54, v49
	v_add_f32_e32 v48, v186, v48
	v_add_f32_e32 v48, v52, v48
	v_exp_f32_e32 v0, v0
	v_add_f32_e32 v48, v53, v48
	v_add_f32_e32 v190, v54, v48
	v_fma_f32 v48, v55, s37, -v15
	v_exp_f32_e32 v55, v48
	v_fma_f32 v48, v56, s37, -v15
	v_exp_f32_e32 v56, v48
	v_pk_mul_f32 v[46:47], v[46:47], v[0:1] op_sel_hi:[1,0]
	v_pk_mul_f32 v[44:45], v[44:45], v[0:1] op_sel_hi:[1,0]
	v_pk_mul_f32 v[42:43], v[42:43], v[0:1] op_sel_hi:[1,0]
	v_pk_mul_f32 v[40:41], v[40:41], v[0:1] op_sel_hi:[1,0]
	v_pk_mul_f32 v[38:39], v[38:39], v[0:1] op_sel_hi:[1,0]
	v_pk_mul_f32 v[36:37], v[36:37], v[0:1] op_sel_hi:[1,0]
	v_pk_mul_f32 v[34:35], v[34:35], v[0:1] op_sel_hi:[1,0]
	v_pk_mul_f32 v[32:33], v[32:33], v[0:1] op_sel_hi:[1,0]
	v_cvt_pk_bf16_f32 v48, v65, v64
; #define MFMA(a, b, c) __builtin_amdgcn_mfma_f32_32x32x16_bf16((a), (b), (c), 0, 0, 0)
; DI unsigned pack2(float a, float b) { f32x2_t v = {a, b}; bf16x2_t r = __builtin_convertvector(v, bf16x2_t); return __builtin_bit_cast(unsigned, r); }
; DI float fexp2(float x) { return __builtin_amdgcn_exp2f(x); }
; DI float shx(float v, int m) { return __shfl_xor(v, m, 64); }
; template <int DQK, bool MASKED, int MODE, class MF>
; DI void attn_step(const bf16_t* sK, const bf16_t* sVt, const bf16x8 (&qf)[DQK / 16], f32x16& o0, f32x16& o1, float& m, float& l,
;                   float sc, const MF& mf, int lane, f32x16 (&s)[2], float invl, bool lanevalid = true) {
;     ...
; #pragma unroll
;   for (int sub = 0; sub < 2; ++sub)
; #pragma unroll
;     for (int q = 0; q < 16; ++q) {
;       float pv = fexp2(__builtin_fmaf(s[sub][q], sc, -moff));
;       if (MASKED && MODE != 0) pv = (s[sub][q] > -1.0e38f) ? pv : 0.f;
;       if (MODE == 2) pv *= invl;
;       s[sub][q] = pv;
;       ps += pv;
;     }
;   if (MODE != 2) {
;     ps += shx(ps, 32);
;     l = l * alpha + ps;
;   }
;   if (MODE == 1) return;
;   if (MODE == 0) {
; #pragma unroll
;     for (int q = 0; q < 16; ++q) { o0[q] *= alpha; o1[q] *= alpha; }
;   }
; #pragma unroll
;   for (int sub = 0; sub < 2; ++sub)
; #pragma unroll
;     for (int s2 = 0; s2 < 2; ++s2) {
;       union { bf16x8 v; unsigned u[4]; } pb;
; #pragma unroll
;       for (int e = 0; e < 4; ++e) pb.u[e] = pack2(s[sub][8 * s2 + 2 * e], s[sub][8 * s2 + 2 * e + 1]);
;       o0 = MFMA(vf[sub][s2][0], pb.v, o0);
;       o1 = MFMA(vf[sub][s2][1], pb.v, o1);
;     }
; DI void phase_attn_mla(const Params& P, bf16_t* og, unsigned char* smem, int L, int G) {
;     ...
;         if (key0 + 63 > t0) attn_step<96, true, 0>(sK + cb * KVB96, sVt + cb * KVB96, qf, o0, o1, m, l, sc, mf, lane, s, 0.f);
	v_cvt_pk_bf16_f32 v49, v66, v67
	v_cvt_pk_bf16_f32 v50, v68, v69
	v_cvt_pk_bf16_f32 v51, v70, v71
	v_pk_mul_f32 v[30:31], v[30:31], v[0:1] op_sel_hi:[1,0]
	v_pk_mul_f32 v[28:29], v[28:29], v[0:1] op_sel_hi:[1,0]
	v_mfma_f32_32x32x16_bf16 v[32:47], v[132:135], v[48:51], v[32:47]
	v_mul_f32_e64 v26, v26, v0
	v_mul_f32_e64 v27, v27, v0
	v_mul_f32_e64 v24, v24, v0
	v_mul_f32_e64 v25, v25, v0
	v_mul_f32_e64 v22, v22, v0
	v_mul_f32_e64 v23, v23, v0
	v_pk_mul_f32 v[20:21], v[20:21], v[0:1] op_sel_hi:[1,0]
	v_pk_mul_f32 v[18:19], v[18:19], v[0:1] op_sel_hi:[1,0]
	v_pk_mul_f32 v[16:17], v[16:17], v[0:1] op_sel_hi:[1,0]
	v_fma_f32 v57, v57, s37, -v15
	v_exp_f32_e32 v57, v57
	v_mfma_f32_32x32x16_bf16 v[16:31], v[128:131], v[48:51], v[16:31]
	v_add_f32_e32 v48, v55, v190
	v_add_f32_e32 v64, v56, v48
	v_cvt_pk_bf16_f32 v48, v72, v73
	v_cvt_pk_bf16_f32 v49, v74, v75
	v_cvt_pk_bf16_f32 v50, v76, v77
	v_cvt_pk_bf16_f32 v51, v78, v79
	v_fma_f32 v58, v58, s37, -v15
	v_exp_f32_e32 v58, v58
	v_mfma_f32_32x32x16_bf16 v[32:47], v[124:127], v[48:51], v[32:47]
	v_fma_f32 v59, v59, s37, -v15
	v_exp_f32_e32 v59, v59
	v_add_f32_e32 v64, v57, v64
	v_add_f32_e32 v64, v58, v64
	v_add_f32_e32 v64, v59, v64
	v_mfma_f32_32x32x16_bf16 v[16:31], v[120:123], v[48:51], v[16:31]
	v_fma_f32 v48, v60, s37, -v15
	v_exp_f32_e32 v60, v48
	v_cvt_pk_bf16_f32 v48, v187, v188
	v_cvt_pk_bf16_f32 v49, v189, v186
	v_cvt_pk_bf16_f32 v50, v52, v53
	v_cvt_pk_bf16_f32 v51, v54, v55
	v_fma_f32 v53, v61, s37, -v15
	v_exp_f32_e32 v53, v53
	v_mfma_f32_32x32x16_bf16 v[32:47], v[116:119], v[48:51], v[32:47]
	v_fma_f32 v54, v62, s37, -v15
	v_exp_f32_e32 v54, v54
	v_fma_f32 v55, v63, s37, -v15
	v_exp_f32_e32 v55, v55
	v_add_f32_e32 v52, v60, v64
	v_mov_b32_e32 v186, v15
	v_mfma_f32_32x32x16_bf16 v[16:31], v[10:13], v[48:51], v[16:31]
	v_add_f32_e32 v10, v53, v52
	v_add_f32_e32 v10, v54, v10
	v_add_f32_e32 v48, v55, v10
	v_cvt_pk_bf16_f32 v10, v56, v57
	v_cvt_pk_bf16_f32 v11, v58, v59
	v_cvt_pk_bf16_f32 v12, v60, v53
	v_cvt_pk_bf16_f32 v13, v54, v55
	s_nop 1
	v_mfma_f32_32x32x16_bf16 v[32:47], v[6:9], v[10:13], v[32:47]
	s_nop 1
	v_mfma_f32_32x32x16_bf16 v[16:31], v[2:5], v[10:13], v[16:31]
	v_fma_f32 v6, v165, v0, v48
	v_mov_b32_e32 v165, v6
.LBB0_788:
	s_andn2_saveexec_b64 s[24:25], s[24:25]
	s_cbranch_execz .LBB0_790
	v_lshl_add_u32 v14, s40, 1, v176
	ds_read_b128 v[2:5], v14
	ds_read_b128 v[6:9], v14 offset:32
	ds_read_b128 v[10:13], v14 offset:64
	ds_read_b128 v[116:119], v14 offset:96
	ds_read_b128 v[120:123], v14 offset:128
	ds_read_b128 v[124:127], v14 offset:160
	ds_read_b128 v[48:51], v14 offset:6656
	ds_read_b128 v[128:131], v14 offset:6688
	ds_read_b128 v[132:135], v14 offset:6720
	ds_read_b128 v[188:191], v14 offset:6752
	ds_read_b128 v[194:197], v14 offset:6784
	ds_read_b128 v[198:201], v14 offset:6816
	s_waitcnt lgkmcnt(11)
	v_mfma_f32_32x32x16_bf16 v[64:79], v[2:5], v[100:103], 0
	v_lshlrev_b32_e32 v2, 1, v175
	v_add3_u32 v3, s39, v172, v2
	v_add3_u32 v2, s39, v173, v2
	s_waitcnt lgkmcnt(10)
	v_mfma_f32_32x32x16_bf16 v[64:79], v[6:9], v[80:83], v[64:79]
	s_waitcnt lgkmcnt(5)
	v_mfma_f32_32x32x16_bf16 v[48:63], v[48:51], v[100:103], 0
	v_mfma_f32_32x32x16_bf16 v[64:79], v[10:13], v[84:87], v[64:79]
	s_waitcnt lgkmcnt(4)
	v_mfma_f32_32x32x16_bf16 v[48:63], v[128:131], v[80:83], v[48:63]
	v_mfma_f32_32x32x16_bf16 v[64:79], v[116:119], v[88:91], v[64:79]
	s_waitcnt lgkmcnt(3)
	v_mfma_f32_32x32x16_bf16 v[48:63], v[132:135], v[84:87], v[48:63]
	v_mfma_f32_32x32x16_bf16 v[64:79], v[120:123], v[92:95], v[64:79]
	s_waitcnt lgkmcnt(2)
	v_mfma_f32_32x32x16_bf16 v[48:63], v[188:191], v[88:91], v[48:63]
	v_mfma_f32_32x32x16_bf16 v[64:79], v[124:127], v[96:99], v[64:79]
	ds_read_b128 v[132:135], v3 offset:13312
	ds_read_b128 v[124:127], v3 offset:13344
	ds_read_b128 v[128:131], v2 offset:13312
	ds_read_b128 v[120:123], v2 offset:13344
	ds_read_b128 v[116:119], v3 offset:13376
	ds_read_b128 v[6:9], v3 offset:13408
	ds_read_b128 v[10:13], v2 offset:13376
	ds_read_b128 v[2:5], v2 offset:13408
	s_waitcnt lgkmcnt(9)
	v_mfma_f32_32x32x16_bf16 v[48:63], v[194:197], v[92:95], v[48:63]
	s_waitcnt lgkmcnt(8)
	v_mfma_f32_32x32x16_bf16 v[48:63], v[198:201], v[96:99], v[48:63]
	v_add_u32_e32 v14, s14, v175
	v_cmp_le_i32_e32 vcc, v14, v164
	s_nop 1
	v_cndmask_b32_e32 v15, v185, v64, vcc
	v_cmp_lt_i32_e32 vcc, v14, v164
	s_nop 1
	v_cndmask_b32_e32 v64, v185, v65, vcc
	v_add_u32_e32 v65, 2, v14
	v_cmp_le_i32_e32 vcc, v65, v164
	s_nop 1
	v_cndmask_b32_e32 v65, v185, v66, vcc
	v_add_u32_e32 v66, 3, v14
	v_cmp_le_i32_e32 vcc, v66, v164
	s_nop 1
	v_cndmask_b32_e32 v66, v185, v67, vcc
	v_add_u32_e32 v67, 4, v14
	v_cmp_le_i32_e32 vcc, v67, v164
	s_nop 1
	v_cndmask_b32_e32 v67, v185, v68, vcc
	v_add_u32_e32 v68, 5, v14
	v_cmp_le_i32_e32 vcc, v68, v164
	s_nop 1
	v_cndmask_b32_e32 v68, v185, v69, vcc
	v_add_u32_e32 v69, 6, v14
	v_cmp_le_i32_e32 vcc, v69, v164
	s_nop 1
	v_cndmask_b32_e32 v69, v185, v70, vcc
	v_add_u32_e32 v70, s14, v174
	v_or_b32_e32 v187, 7, v70
	v_cmp_le_i32_e32 vcc, v187, v164
	v_add_u32_e32 v187, 16, v14
	s_nop 0
	v_cndmask_b32_e32 v71, v185, v71, vcc
	v_cmp_le_i32_e32 vcc, v187, v164
	v_add_u32_e32 v187, 17, v14
	s_nop 0
	v_cndmask_b32_e32 v72, v185, v72, vcc
	v_cmp_le_i32_e32 vcc, v187, v164
	v_add_u32_e32 v187, 18, v14
	s_nop 0
	v_cndmask_b32_e32 v73, v185, v73, vcc
	v_cmp_le_i32_e32 vcc, v187, v164
	v_add_u32_e32 v187, 19, v14
	s_nop 0
	v_cndmask_b32_e32 v74, v185, v74, vcc
	v_cmp_le_i32_e32 vcc, v187, v164
	v_add_u32_e32 v187, 20, v14
	s_nop 0
	v_cndmask_b32_e32 v75, v185, v75, vcc
	v_cmp_le_i32_e32 vcc, v187, v164
	v_add_u32_e32 v187, 21, v14
	s_nop 0
	v_cndmask_b32_e32 v76, v185, v76, vcc
; DI float shx(float v, int m) { return __shfl_xor(v, m, 64); }
; template <int DQK, bool MASKED, int MODE, class MF>
; DI void attn_step(const bf16_t* sK, const bf16_t* sVt, const bf16x8 (&qf)[DQK / 16], f32x16& o0, f32x16& o1, float& m, float& l,
;                   float sc, const MF& mf, int lane, f32x16 (&s)[2], float invl, bool lanevalid = true) {
;     ...
; #pragma unroll
;   for (int sub = 0; sub < 2; ++sub)
; #pragma unroll
;     for (int q = 0; q < 16; ++q) {
;       if (MASKED) { const int kk = sub * 32 + 16 * (q >> 3) + 8 * h + (q & 7); s[sub][q] = mf(kk) ? s[sub][q] : -3.0e38f; }
;       if (MODE != 2) mxr = fmaxf(mxr, s[sub][q]);
;     }
;   float alpha = 1.f;
;   if (MODE != 2) {
;     float mx = fmaxf(m, mxr * sc);
;     mx = fmaxf(mx, shx(mx, 32));
	v_cmp_le_i32_e32 vcc, v187, v164
	v_add_u32_e32 v187, 22, v14
	s_nop 0
	v_cndmask_b32_e32 v77, v185, v77, vcc
	v_cmp_le_i32_e32 vcc, v187, v164
	v_or_b32_e32 v187, 23, v70
	s_nop 0
	v_cndmask_b32_e32 v78, v185, v78, vcc
	v_cmp_le_i32_e32 vcc, v187, v164
	v_add_u32_e32 v187, 32, v14
	s_nop 0
	v_cndmask_b32_e32 v79, v185, v79, vcc
	v_cmp_le_i32_e32 vcc, v187, v164
	v_add_u32_e32 v187, 33, v14
	s_nop 0
	v_cndmask_b32_e32 v48, v185, v48, vcc
	v_cmp_le_i32_e32 vcc, v187, v164
	v_add_u32_e32 v187, 34, v14
	s_nop 0
	v_cndmask_b32_e32 v49, v185, v49, vcc
	v_cmp_le_i32_e32 vcc, v187, v164
	v_add_u32_e32 v187, 35, v14
	s_nop 0
	v_cndmask_b32_e32 v50, v185, v50, vcc
	v_cmp_le_i32_e32 vcc, v187, v164
	v_add_u32_e32 v187, 36, v14
	s_nop 0
	v_cndmask_b32_e32 v51, v185, v51, vcc
	v_cmp_le_i32_e32 vcc, v187, v164
	v_add_u32_e32 v187, 37, v14
	s_nop 0
	v_cndmask_b32_e32 v52, v185, v52, vcc
	v_cmp_le_i32_e32 vcc, v187, v164
	v_add_u32_e32 v187, 38, v14
	s_nop 0
	v_cndmask_b32_e32 v53, v185, v53, vcc
	v_cmp_le_i32_e32 vcc, v187, v164
	v_or_b32_e32 v187, 39, v70
	s_nop 0
	v_cndmask_b32_e32 v54, v185, v54, vcc
	v_cmp_le_i32_e32 vcc, v187, v164
	v_add_u32_e32 v187, 48, v14
	s_nop 0
	v_cndmask_b32_e32 v55, v185, v55, vcc
	v_cmp_le_i32_e32 vcc, v187, v164
	v_add_u32_e32 v187, 49, v14
	s_nop 0
	v_cndmask_b32_e32 v56, v185, v56, vcc
	v_cmp_le_i32_e32 vcc, v187, v164
	v_add_u32_e32 v187, 50, v14
	s_nop 0
	v_cndmask_b32_e32 v57, v185, v57, vcc
	v_cmp_le_i32_e32 vcc, v187, v164
	v_add_u32_e32 v187, 51, v14
	s_nop 0
	v_cndmask_b32_e32 v58, v185, v58, vcc
	v_cmp_le_i32_e32 vcc, v187, v164
	v_add_u32_e32 v187, 52, v14
	s_nop 0
	v_cndmask_b32_e32 v59, v185, v59, vcc
	v_cmp_le_i32_e32 vcc, v187, v164
	v_add_u32_e32 v187, 53, v14
	v_add_u32_e32 v14, 54, v14
	v_cndmask_b32_e32 v60, v185, v60, vcc
	v_cmp_le_i32_e32 vcc, v187, v164
	s_nop 1
	v_cndmask_b32_e32 v61, v185, v61, vcc
	v_cmp_le_i32_e32 vcc, v14, v164
	s_nop 1
	v_cndmask_b32_e32 v14, v185, v62, vcc
	v_or_b32_e32 v62, 55, v70
	v_cmp_le_i32_e32 vcc, v62, v164
	s_nop 1
	v_cndmask_b32_e32 v62, v185, v63, vcc
	v_max3_f32 v63, v15, s36, v64
	v_max3_f32 v63, v63, v65, v66
	v_max3_f32 v63, v63, v67, v68
	v_max3_f32 v63, v63, v69, v71
	v_max3_f32 v63, v63, v72, v73
	v_max3_f32 v63, v63, v74, v75
	v_max3_f32 v63, v63, v76, v77
	v_max3_f32 v63, v63, v78, v79
	v_max3_f32 v63, v63, v48, v49
	v_max3_f32 v63, v63, v50, v51
	v_max3_f32 v63, v63, v52, v53
	v_max3_f32 v63, v63, v54, v55
	v_max3_f32 v63, v63, v56, v57
	v_max3_f32 v63, v63, v58, v59
	v_max3_f32 v63, v63, v60, v61
	v_max3_f32 v63, v63, v14, v62
	v_mul_f32_e32 v63, 0x3e16c740, v63
	v_cmp_lt_i32_e32 vcc, v183, v184
	v_max_f32_e32 v0, v0, v63
	s_nop 0
	v_cndmask_b32_e32 v63, v182, v183, vcc
	v_lshlrev_b32_e32 v63, 2, v63
	ds_bpermute_b32 v70, v63, v0
	s_waitcnt lgkmcnt(0)
; #define MFMA(a, b, c) __builtin_amdgcn_mfma_f32_32x32x16_bf16((a), (b), (c), 0, 0, 0)
; DI unsigned pack2(float a, float b) { f32x2_t v = {a, b}; bf16x2_t r = __builtin_convertvector(v, bf16x2_t); return __builtin_bit_cast(unsigned, r); }
; DI float fexp2(float x) { return __builtin_amdgcn_exp2f(x); }
; DI float shx(float v, int m) { return __shfl_xor(v, m, 64); }
; template <int DQK, bool MASKED, int MODE, class MF>
; DI void attn_step(const bf16_t* sK, const bf16_t* sVt, const bf16x8 (&qf)[DQK / 16], f32x16& o0, f32x16& o1, float& m, float& l,
;                   float sc, const MF& mf, int lane, f32x16 (&s)[2], float invl, bool lanevalid = true) {
;     ...
;   float alpha = 1.f;
;   if (MODE != 2) {
;     float mx = fmaxf(m, mxr * sc);
;     mx = fmaxf(mx, shx(mx, 32));
;     if (!MASKED) mx = lanevalid ? mx : m;
;     alpha = fexp2(m - mx);
;     m = mx;
;   }
;   const float moff = (!MASKED && !lanevalid) ? 1.0e30f : m;
;   float ps = 0.f;
; #pragma unroll
;   for (int sub = 0; sub < 2; ++sub)
; #pragma unroll
;     for (int q = 0; q < 16; ++q) {
;       float pv = fexp2(__builtin_fmaf(s[sub][q], sc, -moff));
;       if (MASKED && MODE != 0) pv = (s[sub][q] > -1.0e38f) ? pv : 0.f;
;       if (MODE == 2) pv *= invl;
;       s[sub][q] = pv;
;       ps += pv;
;     }
;   if (MODE != 2) {
;     ps += shx(ps, 32);
;     l = l * alpha + ps;
;   }
;   if (MODE == 1) return;
;   if (MODE == 0) {
; #pragma unroll
;     for (int q = 0; q < 16; ++q) { o0[q] *= alpha; o1[q] *= alpha; }
;   }
; #pragma unroll
;   for (int sub = 0; sub < 2; ++sub)
; #pragma unroll
;     for (int s2 = 0; s2 < 2; ++s2) {
;       union { bf16x8 v; unsigned u[4]; } pb;
; #pragma unroll
;       for (int e = 0; e < 4; ++e) pb.u[e] = pack2(s[sub][8 * s2 + 2 * e], s[sub][8 * s2 + 2 * e + 1]);
;       o0 = MFMA(vf[sub][s2][0], pb.v, o0);
;       o1 = MFMA(vf[sub][s2][1], pb.v, o1);
;     }
	ds_write_b32 v252, v254
	v_max_f32_e32 v70, v70, v70
	v_max_f32_e32 v70, v0, v70
	v_fma_f32 v0, v15, s37, -v70
	v_exp_f32_e32 v15, v0
	v_fma_f32 v0, v64, s37, -v70
	v_exp_f32_e32 v64, v0
	v_fma_f32 v0, v65, s37, -v70
	v_exp_f32_e32 v65, v0
	v_fma_f32 v66, v66, s37, -v70
	v_exp_f32_e32 v66, v66
	v_fma_f32 v67, v67, s37, -v70
	v_sub_f32_e32 v0, v186, v70
	v_add_f32_e32 v186, 0, v15
	v_exp_f32_e32 v67, v67
	v_fma_f32 v68, v68, s37, -v70
	v_add_f32_e32 v186, v64, v186
	v_exp_f32_e32 v68, v68
	v_fma_f32 v69, v69, s37, -v70
	v_add_f32_e32 v186, v65, v186
	v_exp_f32_e32 v69, v69
	v_fma_f32 v71, v71, s37, -v70
	v_add_f32_e32 v186, v66, v186
	v_exp_f32_e32 v71, v71
	v_fma_f32 v72, v72, s37, -v70
	v_add_f32_e32 v186, v67, v186
	v_exp_f32_e32 v72, v72
	v_fma_f32 v73, v73, s37, -v70
	v_add_f32_e32 v186, v68, v186
	v_exp_f32_e32 v73, v73
	v_fma_f32 v74, v74, s37, -v70
	v_add_f32_e32 v186, v69, v186
	v_exp_f32_e32 v74, v74
	v_fma_f32 v75, v75, s37, -v70
	v_add_f32_e32 v186, v71, v186
	v_exp_f32_e32 v75, v75
	v_fma_f32 v76, v76, s37, -v70
	v_add_f32_e32 v186, v72, v186
	v_exp_f32_e32 v76, v76
	v_fma_f32 v77, v77, s37, -v70
	v_add_f32_e32 v186, v73, v186
	v_exp_f32_e32 v77, v77
	v_fma_f32 v78, v78, s37, -v70
	v_add_f32_e32 v186, v74, v186
	v_exp_f32_e32 v78, v78
	v_fma_f32 v79, v79, s37, -v70
	v_add_f32_e32 v186, v75, v186
	v_exp_f32_e32 v79, v79
	v_fma_f32 v48, v48, s37, -v70
	v_add_f32_e32 v186, v76, v186
	v_exp_f32_e32 v187, v48
	v_fma_f32 v48, v49, s37, -v70
	v_add_f32_e32 v186, v77, v186
	v_exp_f32_e32 v188, v48
	v_fma_f32 v48, v50, s37, -v70
	v_add_f32_e32 v186, v78, v186
	v_exp_f32_e32 v189, v48
	v_fma_f32 v49, v51, s37, -v70
	v_add_f32_e32 v48, v79, v186
	v_exp_f32_e32 v186, v49
	v_fma_f32 v49, v52, s37, -v70
	v_add_f32_e32 v48, v187, v48
	v_exp_f32_e32 v52, v49
	v_fma_f32 v49, v53, s37, -v70
	v_add_f32_e32 v48, v188, v48
	v_exp_f32_e32 v53, v49
	v_fma_f32 v49, v54, s37, -v70
	v_add_f32_e32 v48, v189, v48
	v_exp_f32_e32 v54, v49
	v_add_f32_e32 v48, v186, v48
	v_add_f32_e32 v48, v52, v48
	v_exp_f32_e32 v0, v0
	v_add_f32_e32 v48, v53, v48
	v_add_f32_e32 v190, v54, v48
	v_fma_f32 v48, v55, s37, -v70
	v_exp_f32_e32 v55, v48
	v_fma_f32 v48, v56, s37, -v70
	v_exp_f32_e32 v56, v48
	v_pk_mul_f32 v[46:47], v[46:47], v[0:1] op_sel_hi:[1,0]
	v_pk_mul_f32 v[44:45], v[44:45], v[0:1] op_sel_hi:[1,0]
	v_pk_mul_f32 v[42:43], v[42:43], v[0:1] op_sel_hi:[1,0]
	v_pk_mul_f32 v[40:41], v[40:41], v[0:1] op_sel_hi:[1,0]
	v_pk_mul_f32 v[38:39], v[38:39], v[0:1] op_sel_hi:[1,0]
	v_pk_mul_f32 v[36:37], v[36:37], v[0:1] op_sel_hi:[1,0]
	v_pk_mul_f32 v[34:35], v[34:35], v[0:1] op_sel_hi:[1,0]
	v_pk_mul_f32 v[32:33], v[32:33], v[0:1] op_sel_hi:[1,0]
	v_pk_mul_f32 v[30:31], v[30:31], v[0:1] op_sel_hi:[1,0]
	v_cvt_pk_bf16_f32 v48, v15, v64
	v_cvt_pk_bf16_f32 v49, v65, v66
	v_cvt_pk_bf16_f32 v50, v67, v68
	v_cvt_pk_bf16_f32 v51, v69, v71
	v_pk_mul_f32 v[28:29], v[28:29], v[0:1] op_sel_hi:[1,0]
	v_pk_mul_f32 v[26:27], v[26:27], v[0:1] op_sel_hi:[1,0]
	v_pk_mul_f32 v[24:25], v[24:25], v[0:1] op_sel_hi:[1,0]
	v_pk_mul_f32 v[22:23], v[22:23], v[0:1] op_sel_hi:[1,0]
	v_pk_mul_f32 v[20:21], v[20:21], v[0:1] op_sel_hi:[1,0]
	v_pk_mul_f32 v[18:19], v[18:19], v[0:1] op_sel_hi:[1,0]
	v_pk_mul_f32 v[16:17], v[16:17], v[0:1] op_sel_hi:[1,0]
	v_mfma_f32_32x32x16_bf16 v[32:47], v[132:135], v[48:51], v[32:47]
	v_fma_f32 v57, v57, s37, -v70
	v_exp_f32_e32 v57, v57
	v_fma_f32 v58, v58, s37, -v70
	v_exp_f32_e32 v58, v58
	v_fma_f32 v59, v59, s37, -v70
	v_add_f32_e32 v15, v55, v190
	v_exp_f32_e32 v59, v59
	v_mfma_f32_32x32x16_bf16 v[16:31], v[128:131], v[48:51], v[16:31]
	v_cvt_pk_bf16_f32 v48, v72, v73
	v_cvt_pk_bf16_f32 v49, v74, v75
	v_cvt_pk_bf16_f32 v50, v76, v77
	v_cvt_pk_bf16_f32 v51, v78, v79
	v_add_f32_e32 v15, v56, v15
	v_add_f32_e32 v15, v57, v15
	v_fma_f32 v14, v14, s37, -v70
	v_mfma_f32_32x32x16_bf16 v[32:47], v[124:127], v[48:51], v[32:47]
	v_add_f32_e32 v15, v58, v15
	v_exp_f32_e32 v14, v14
	v_add_f32_e32 v15, v59, v15
	v_mfma_f32_32x32x16_bf16 v[16:31], v[120:123], v[48:51], v[16:31]
	v_fma_f32 v48, v60, s37, -v70
	v_exp_f32_e32 v60, v48
	v_cvt_pk_bf16_f32 v48, v187, v188
	v_cvt_pk_bf16_f32 v49, v189, v186
	v_cvt_pk_bf16_f32 v50, v52, v53
	v_cvt_pk_bf16_f32 v51, v54, v55
	v_fma_f32 v52, v61, s37, -v70
	v_exp_f32_e32 v52, v52
	v_mfma_f32_32x32x16_bf16 v[32:47], v[116:119], v[48:51], v[32:47]
	v_fma_f32 v53, v62, s37, -v70
	v_exp_f32_e32 v53, v53
	v_add_f32_e32 v15, v60, v15
	v_mov_b32_e32 v186, v70
	v_mfma_f32_32x32x16_bf16 v[16:31], v[10:13], v[48:51], v[16:31]
	v_add_f32_e32 v10, v52, v15
	v_add_f32_e32 v10, v14, v10
	v_add_f32_e32 v15, v53, v10
	v_cvt_pk_bf16_f32 v10, v56, v57
	v_cvt_pk_bf16_f32 v11, v58, v59
	v_cvt_pk_bf16_f32 v12, v60, v52
	v_cvt_pk_bf16_f32 v13, v14, v53
	s_nop 1
	v_mfma_f32_32x32x16_bf16 v[32:47], v[6:9], v[10:13], v[32:47]
	s_nop 1
	v_mfma_f32_32x32x16_bf16 v[16:31], v[2:5], v[10:13], v[16:31]
	v_fma_f32 v6, v165, v0, v15
	v_mov_b32_e32 v165, v6
